# Strategy 9 loop-edge edit: MLA attention KV-tile loop, second unmasked tile body renamed to the first body's register roles, the two per-tile accumulator copy blocks (16 v_mov_b64 + 2 v_mov_b32 each)
# speedup vs baseline: 1.0139x; 1.0139x over previous
; template <int DQK, bool WIN>
; DI void attn_item(const u16* __restrict__ Qb, int ldq, const u16* __restrict__ Kb, int ldk, const u16* __restrict__ Vtb, int qb,
;                   float qscale, float sink2, const u16* __restrict__ zb, int ldz, u16* __restrict__ ob, int ldo, u16* lds) {
;     ...
;       if (__any(mn != m)) {
;         const float alpha = __builtin_amdgcn_exp2f((m - mn) * qscale);
;         lsum *= alpha;
; #pragma unroll
;         for (int i = 0; i < 16; ++i) { o[0][i] *= alpha; o[1][i] *= alpha; }
;       }
;       m = mn;
;     ...
;     if (WIN || kt >= 2 * qb) tile_body(kt, 0, std::true_type{}); else tile_body(kt, 0, std::false_type{});
.LBB0_238:
	s_or_b64 exec, exec, s[24:25]
	s_nop 1
	v_mov_b64_e32 v[18:19], v[34:35]
	s_nop 8
	v_mov_b64_e32 v[2:3], v[50:51]
	v_mov_b64_e32 v[20:21], v[36:37]
	v_mov_b64_e32 v[22:23], v[38:39]
	v_mov_b64_e32 v[24:25], v[40:41]
	v_mov_b64_e32 v[26:27], v[42:43]
	v_mov_b64_e32 v[28:29], v[44:45]
	v_mov_b64_e32 v[30:31], v[46:47]
	v_mov_b64_e32 v[32:33], v[48:49]
	s_nop 0
	v_mov_b64_e32 v[4:5], v[52:53]
	v_mov_b64_e32 v[6:7], v[54:55]
	v_mov_b64_e32 v[8:9], v[56:57]
	v_mov_b64_e32 v[10:11], v[58:59]
	v_mov_b64_e32 v[12:13], v[60:61]
	v_mov_b64_e32 v[14:15], v[62:63]
	v_mov_b64_e32 v[16:17], v[64:65]
	v_mov_b32_e32 v142, v0
	v_mov_b32_e32 v157, v158
	s_mov_b64 s[24:25], 0

; #define MFMA32(a, b, c) __builtin_amdgcn_mfma_f32_32x32x16_bf16((a), (b), (c), 0, 0, 0)
; template <int DQK, bool WIN>
; DI void attn_item(const u16* __restrict__ Qb, int ldq, const u16* __restrict__ Kb, int ldk, const u16* __restrict__ Vtb, int qb,
;                   float qscale, float sink2, const u16* __restrict__ zb, int ldz, u16* __restrict__ ob, int ldo, u16* lds) {
;     ...
;       f32x16 st[2];
; #pragma unroll
;       for (int kb = 0; kb < 2; ++kb) {
; #pragma unroll
;         for (int i = 0; i < 16; ++i) st[kb][i] = 0.f;
; #pragma unroll
;         for (int s = 0; s < NKS; ++s) {
;           bf16x8 a = *(const bf16x8*)(ks + (kb * 32 + r) * KST + 16 * s + 8 * hh);
;           st[kb] = MFMA32(a, qf[s], st[kb]);
;         }
;       }
;     ...
;     swrite(rkB, rvB, 1);
;     __syncthreads();
;     if (kt + 3 <= kt_hi) gload(rkB, rvB, kt + 3);
;     if (WIN || kt + 1 >= 2 * qb) tile_body(kt + 1, 1, std::true_type{}); else tile_body(kt + 1, 1, std::false_type{});
.LBB0_245:
	v_add_u32_e32 v34, 0x8800, v150
	s_add_i32 s34, s31, 2
	s_waitcnt vmcnt(4)
	ds_write_b128 v147, v[102:105] offset:22528
	s_waitcnt vmcnt(3)
	ds_write_b128 v148, v[106:109] offset:22528
	s_waitcnt vmcnt(2)
	ds_write_b128 v149, v[110:113] offset:22528
	s_waitcnt vmcnt(1)
	ds_write2_b64 v34, v[114:115], v[116:117] offset0:128 offset1:130
	v_add_u32_e32 v34, 0x8800, v152
	s_cmp_gt_u32 s34, s30
	s_waitcnt vmcnt(0)
	ds_write2_b64 v34, v[118:119], v[120:121] offset0:128 offset1:130
	s_waitcnt lgkmcnt(0)
	s_barrier
	s_cbranch_scc1 .LBB0_247
	v_add_u32_e32 v34, s20, v143
	v_mad_i64_i32 v[34:35], s[0:1], v34, s96, v[136:137]
	v_add_u32_e32 v36, s20, v144
	v_mad_i64_i32 v[36:37], s[0:1], v36, s96, v[138:139]
	global_load_dwordx4 v[102:105], v[34:35], off
	global_load_dwordx4 v[106:109], v[36:37], off
	v_add_u32_e32 v34, s20, v145
	v_mad_i64_i32 v[34:35], s[0:1], v34, s96, v[140:141]
	s_mov_b32 s21, s53
	s_lshl_b64 s[0:1], s[20:21], 1
	global_load_dwordx4 v[110:113], v[34:35], off
	v_lshl_add_u64 v[34:35], v[132:133], 0, s[0:1]
	v_lshl_add_u64 v[36:37], v[134:135], 0, s[0:1]
	global_load_dwordx4 v[114:117], v[34:35], off
	global_load_dwordx4 v[118:121], v[36:37], off
.LBB0_247:
	s_add_i32 s0, s20, 0xffffff80
	s_cmp_lt_u32 s31, s29
	v_cmp_le_i32_e64 s[8:9], s0, v154
	s_mov_b64 s[24:25], -1
	s_cbranch_scc1 .LBB0_257
	v_mov_b64_e32 v[50:51], v[2:3]
	v_mov_b64_e32 v[34:35], v[18:19]
	v_mov_b32_e32 v158, v157
	v_mov_b32_e32 v0, v142
	v_mov_b64_e32 v[52:53], v[4:5]
	v_mov_b64_e32 v[54:55], v[6:7]
	v_mov_b64_e32 v[56:57], v[8:9]
	v_mov_b64_e32 v[58:59], v[10:11]
	v_mov_b64_e32 v[60:61], v[12:13]
	v_mov_b64_e32 v[62:63], v[14:15]
	v_mov_b64_e32 v[64:65], v[16:17]
	v_mov_b64_e32 v[36:37], v[20:21]
	v_mov_b64_e32 v[38:39], v[22:23]
	v_mov_b64_e32 v[40:41], v[24:25]
	v_mov_b64_e32 v[42:43], v[26:27]
	v_mov_b64_e32 v[44:45], v[28:29]
	v_mov_b64_e32 v[46:47], v[30:31]
	v_mov_b64_e32 v[48:49], v[32:33]
	s_and_saveexec_b64 s[24:25], s[8:9]
	s_cbranch_execz .LBB0_252
	ds_read_b128 v[206:209], v155 offset:22528
	ds_read_b128 v[210:213], v155 offset:22560
	ds_read_b128 v[214:217], v155 offset:22592
	ds_read_b128 v[218:221], v155 offset:29216
	ds_read_b128 v[222:225], v155 offset:22624
	ds_read_b128 v[226:229], v155 offset:22656
	ds_read_b128 v[230:233], v155 offset:22688
	ds_read_b128 v[234:237], v155 offset:29184
	ds_read_b128 v[238:241], v155 offset:29248
	ds_read_b128 v[242:245], v155 offset:29280
	ds_read_b128 v[246:249], v155 offset:29312
	ds_read_b128 v[250:253], v155 offset:29344
	v_add_u32_e32 v142, s20, v146
	v_add_u32_e32 v157, 0xffffff80, v142
	v_cmp_le_i32_e32 vcc, v157, v130
	s_waitcnt lgkmcnt(11)
	v_mfma_f32_32x32x16_bf16 v[18:33], v[206:209], v[66:69], 0
	s_waitcnt lgkmcnt(10)
	v_mfma_f32_32x32x16_bf16 v[18:33], v[210:213], v[70:73], v[18:33]
	s_waitcnt lgkmcnt(9)
	v_mfma_f32_32x32x16_bf16 v[18:33], v[214:217], v[74:77], v[18:33]
	s_waitcnt lgkmcnt(7)
	v_mfma_f32_32x32x16_bf16 v[18:33], v[222:225], v[78:81], v[18:33]
	s_waitcnt lgkmcnt(6)
	v_mfma_f32_32x32x16_bf16 v[18:33], v[226:229], v[82:85], v[18:33]
	s_waitcnt lgkmcnt(5)
	v_mfma_f32_32x32x16_bf16 v[18:33], v[230:233], v[86:89], v[18:33]
	s_waitcnt lgkmcnt(4)
	v_mfma_f32_32x32x16_bf16 v[2:17], v[234:237], v[66:69], 0
	v_mfma_f32_32x32x16_bf16 v[2:17], v[218:221], v[70:73], v[2:17]
	s_waitcnt lgkmcnt(3)
	v_mfma_f32_32x32x16_bf16 v[2:17], v[238:241], v[74:77], v[2:17]
	s_waitcnt lgkmcnt(2)
	v_mfma_f32_32x32x16_bf16 v[2:17], v[242:245], v[78:81], v[2:17]
	s_waitcnt lgkmcnt(1)
	v_mfma_f32_32x32x16_bf16 v[2:17], v[246:249], v[82:85], v[2:17]
	s_waitcnt lgkmcnt(0)
; #define MFMA32(a, b, c) __builtin_amdgcn_mfma_f32_32x32x16_bf16((a), (b), (c), 0, 0, 0)
; template <int DQK, bool WIN>
; DI void attn_item(const u16* __restrict__ Qb, int ldq, const u16* __restrict__ Kb, int ldk, const u16* __restrict__ Vtb, int qb,
;                   float qscale, float sink2, const u16* __restrict__ zb, int ldz, u16* __restrict__ ob, int ldo, u16* lds) {
;     ...
;           bf16x8 a = *(const bf16x8*)(ks + (kb * 32 + r) * KST + 16 * s + 8 * hh);
;           st[kb] = MFMA32(a, qf[s], st[kb]);
;         }
;       }
;       float mx = -INFINITY;
; #pragma unroll
;       for (int kb = 0; kb < 2; ++kb)
; #pragma unroll
;         for (int i = 0; i < 16; ++i) {
;           float v = st[kb][i];
;           if (MASK) {
;             int kg = k0 + kb * 32 + (i & 3) + 8 * (i >> 2) + 4 * hh;
;             bool ok = kg <= qrow;
;             if (WIN) ok = ok && (qrow - kg < 128);
;             v = ok ? v : -INFINITY;
;             st[kb][i] = v;
;           }
;           mx = fmaxf(mx, v);
;         }
;       mx = fmaxf(mx, __shfl_xor(mx, 32));
;       const float mn = fmaxf(m, mx);
;       if (__any(mn != m)) {
;         const float alpha = __builtin_amdgcn_exp2f((m - mn) * qscale);
;         lsum *= alpha;
; #pragma unroll
;         for (int i = 0; i < 16; ++i) { o[0][i] *= alpha; o[1][i] *= alpha; }
;       }
	v_mfma_f32_32x32x16_bf16 v[2:17], v[250:253], v[86:89], v[2:17]
	s_nop 0
	v_cndmask_b32_e32 v167, v176, v18, vcc
	v_cmp_lt_i32_e32 vcc, v157, v130
	s_nop 1
	v_cndmask_b32_e32 v166, v176, v19, vcc
	v_add_u32_e32 v19, 0xffffff82, v142
	v_cmp_le_i32_e32 vcc, v19, v130
	v_add_u32_e32 v19, 0xffffff83, v142
	v_max3_f32 v18, v167, s94, v166
	v_cndmask_b32_e32 v182, v176, v20, vcc
	v_cmp_le_i32_e32 vcc, v19, v130
	v_add_u32_e32 v19, 0xffffff88, v142
	s_nop 0
	v_cndmask_b32_e32 v183, v176, v21, vcc
	v_cmp_le_i32_e32 vcc, v19, v130
	v_add_u32_e32 v19, 0xffffff89, v142
	v_max3_f32 v18, v18, v182, v183
	v_cndmask_b32_e32 v185, v176, v22, vcc
	v_cmp_le_i32_e32 vcc, v19, v130
	v_add_u32_e32 v19, 0xffffff8a, v142
	s_nop 0
	v_cndmask_b32_e32 v186, v176, v23, vcc
	v_cmp_le_i32_e32 vcc, v19, v130
	v_add_u32_e32 v19, 0xffffff8b, v142
	v_max3_f32 v18, v18, v185, v186
	v_cndmask_b32_e32 v190, v176, v24, vcc
	v_cmp_le_i32_e32 vcc, v19, v130
	v_add_u32_e32 v19, 0xffffff90, v142
	s_nop 0
	v_cndmask_b32_e32 v191, v176, v25, vcc
	v_cmp_le_i32_e32 vcc, v19, v130
	v_add_u32_e32 v19, 0xffffff91, v142
	v_max3_f32 v18, v18, v190, v191
	v_cndmask_b32_e32 v201, v176, v26, vcc
	v_cmp_le_i32_e32 vcc, v19, v130
	v_add_u32_e32 v19, 0xffffff92, v142
	s_nop 0
	v_cndmask_b32_e32 v195, v176, v27, vcc
	v_cmp_le_i32_e32 vcc, v19, v130
	v_add_u32_e32 v19, 0xffffff93, v142
	v_max3_f32 v18, v18, v201, v195
	v_cndmask_b32_e32 v202, v176, v28, vcc
	v_cmp_le_i32_e32 vcc, v19, v130
	v_add_u32_e32 v19, 0xffffff98, v142
	s_nop 0
	v_cndmask_b32_e32 v196, v176, v29, vcc
	v_cmp_le_i32_e32 vcc, v19, v130
	v_add_u32_e32 v19, 0xffffff99, v142
	v_max3_f32 v18, v18, v202, v196
	v_cndmask_b32_e32 v203, v176, v30, vcc
	v_cmp_le_i32_e32 vcc, v19, v130
	v_add_u32_e32 v19, 0xffffff9a, v142
	s_nop 0
	v_cndmask_b32_e32 v197, v176, v31, vcc
	v_cmp_le_i32_e32 vcc, v19, v130
	v_add_u32_e32 v19, 0xffffff9b, v142
	v_max3_f32 v18, v18, v203, v197
	v_cndmask_b32_e32 v204, v176, v32, vcc
	v_cmp_le_i32_e32 vcc, v19, v130
	v_add_u32_e32 v19, 0xffffffa0, v142
	s_nop 0
	v_cndmask_b32_e32 v198, v176, v33, vcc
	v_cmp_le_i32_e32 vcc, v19, v130
	v_max3_f32 v18, v18, v204, v198
	s_nop 0
	v_cndmask_b32_e32 v205, v176, v2, vcc
	v_add_u32_e32 v2, 0xffffffa1, v142
	v_cmp_le_i32_e32 vcc, v2, v130
	s_nop 1
	v_cndmask_b32_e32 v199, v176, v3, vcc
	v_add_u32_e32 v3, 0xffffffa2, v142
	v_cmp_le_i32_e32 vcc, v3, v130
	v_add_u32_e32 v3, 0xffffffa3, v142
	v_max3_f32 v2, v18, v205, v199
	v_cndmask_b32_e32 v200, v176, v4, vcc
	v_cmp_le_i32_e32 vcc, v3, v130
	v_add_u32_e32 v3, 0xffffffa8, v142
	v_and_b32_e32 v4, 64, v172
	v_cndmask_b32_e32 v193, v176, v5, vcc
	v_cmp_le_i32_e32 vcc, v3, v130
	v_add_u32_e32 v3, 0xffffffa9, v142
	v_max3_f32 v2, v2, v200, v193
	v_cndmask_b32_e32 v194, v176, v6, vcc
	v_cmp_le_i32_e32 vcc, v3, v130
	v_add_u32_e32 v3, 0xffffffaa, v142
	v_add_u32_e32 v4, 64, v4
	v_cndmask_b32_e32 v192, v176, v7, vcc
	v_cmp_le_i32_e32 vcc, v3, v130
	v_add_u32_e32 v3, 0xffffffab, v142
	v_max3_f32 v2, v2, v194, v192
	v_cndmask_b32_e32 v187, v176, v8, vcc
	v_cmp_le_i32_e32 vcc, v3, v130
	v_add_u32_e32 v3, 0xffffffb0, v142
	v_mov_b64_e32 v[18:19], v[34:35]
	v_cndmask_b32_e32 v188, v176, v9, vcc
	v_cmp_le_i32_e32 vcc, v3, v130
	v_add_u32_e32 v3, 0xffffffb1, v142
	v_max3_f32 v2, v2, v187, v188
	v_cndmask_b32_e32 v189, v176, v10, vcc
	v_cmp_le_i32_e32 vcc, v3, v130
	v_add_u32_e32 v3, 0xffffffb2, v142
	v_mov_b64_e32 v[20:21], v[36:37]
	v_cndmask_b32_e32 v184, v176, v11, vcc
	v_cmp_le_i32_e32 vcc, v3, v130
	v_add_u32_e32 v3, 0xffffffb3, v142
	v_max3_f32 v2, v2, v189, v184
	v_cndmask_b32_e32 v165, v176, v12, vcc
	v_cmp_le_i32_e32 vcc, v3, v130
	v_add_u32_e32 v3, 0xffffffb8, v142
	v_mov_b64_e32 v[22:23], v[38:39]
	v_cndmask_b32_e32 v164, v176, v13, vcc
	v_cmp_le_i32_e32 vcc, v3, v130
	v_add_u32_e32 v3, 0xffffffb9, v142
	v_max3_f32 v2, v2, v165, v164
	v_cndmask_b32_e32 v160, v176, v14, vcc
	v_cmp_le_i32_e32 vcc, v3, v130
	v_add_u32_e32 v3, 0xffffffba, v142
	v_mov_b64_e32 v[24:25], v[40:41]
	v_cndmask_b32_e32 v161, v176, v15, vcc
	v_cmp_le_i32_e32 vcc, v3, v130
	v_add_u32_e32 v3, 0xffffffbb, v142
	v_max3_f32 v2, v2, v160, v161
	v_cndmask_b32_e32 v162, v176, v16, vcc
	v_cmp_le_i32_e32 vcc, v3, v130
	v_xor_b32_e32 v3, 32, v172
	v_mov_b64_e32 v[26:27], v[42:43]
	v_cndmask_b32_e32 v159, v176, v17, vcc
	v_cmp_lt_i32_e32 vcc, v3, v4
	v_max3_f32 v2, v2, v162, v159
	v_mov_b64_e32 v[28:29], v[44:45]
	v_cndmask_b32_e32 v3, v172, v3, vcc
	v_lshlrev_b32_e32 v3, 2, v3
	v_mov_b32_e32 v3, v2
	s_nop 1
	v_permlane32_swap_b32 v3, v2
	v_mov_b64_e32 v[30:31], v[46:47]
	v_mov_b64_e32 v[32:33], v[48:49]
	v_mov_b32_e32 v142, v0
	s_waitcnt lgkmcnt(0)
	v_max3_f32 v157, v158, v2, v3
	v_mov_b64_e32 v[2:3], v[50:51]
	v_cmp_neq_f32_e32 vcc, v157, v158
	v_mov_b64_e32 v[4:5], v[52:53]
	v_mov_b64_e32 v[6:7], v[54:55]
	v_mov_b64_e32 v[8:9], v[56:57]
	v_mov_b64_e32 v[10:11], v[58:59]
	v_mov_b64_e32 v[12:13], v[60:61]
	v_mov_b64_e32 v[14:15], v[62:63]
	v_mov_b64_e32 v[16:17], v[64:65]
	s_cbranch_vccz .LBB0_251
	v_sub_f32_e32 v2, v158, v157
	v_mul_f32_e32 v2, 0x3e16c740, v2
	v_exp_f32_e32 v2, v2
	s_nop 0
	v_mul_f32_e32 v142, v0, v2
	v_pk_mul_f32 v[32:33], v[48:49], v[2:3] op_sel_hi:[1,0]
	v_pk_mul_f32 v[30:31], v[46:47], v[2:3] op_sel_hi:[1,0]
	v_pk_mul_f32 v[28:29], v[44:45], v[2:3] op_sel_hi:[1,0]
	v_pk_mul_f32 v[26:27], v[42:43], v[2:3] op_sel_hi:[1,0]
	v_pk_mul_f32 v[24:25], v[40:41], v[2:3] op_sel_hi:[1,0]
	v_pk_mul_f32 v[22:23], v[38:39], v[2:3] op_sel_hi:[1,0]
	v_pk_mul_f32 v[20:21], v[36:37], v[2:3] op_sel_hi:[1,0]
	v_pk_mul_f32 v[18:19], v[34:35], v[2:3] op_sel_hi:[1,0]
	v_pk_mul_f32 v[16:17], v[64:65], v[2:3] op_sel_hi:[1,0]
	v_pk_mul_f32 v[14:15], v[62:63], v[2:3] op_sel_hi:[1,0]
	v_pk_mul_f32 v[12:13], v[60:61], v[2:3] op_sel_hi:[1,0]
	v_pk_mul_f32 v[10:11], v[58:59], v[2:3] op_sel_hi:[1,0]
	v_pk_mul_f32 v[8:9], v[56:57], v[2:3] op_sel_hi:[1,0]
	v_pk_mul_f32 v[6:7], v[54:55], v[2:3] op_sel_hi:[1,0]
	v_pk_mul_f32 v[4:5], v[52:53], v[2:3] op_sel_hi:[1,0]
	v_pk_mul_f32 v[2:3], v[50:51], v[2:3] op_sel_hi:[1,0]

; #define MFMA32(a, b, c) __builtin_amdgcn_mfma_f32_32x32x16_bf16((a), (b), (c), 0, 0, 0)
; template <int DQK, bool WIN>
; DI void attn_item(const u16* __restrict__ Qb, int ldq, const u16* __restrict__ Kb, int ldk, const u16* __restrict__ Vtb, int qb,
;                   float qscale, float sink2, const u16* __restrict__ zb, int ldz, u16* __restrict__ ob, int ldo, u16* lds) {
;     ...
; #pragma unroll
;       for (int kb = 0; kb < 2; ++kb) {
; #pragma unroll
;         for (int i = 0; i < 16; ++i) st[kb][i] = 0.f;
; #pragma unroll
;         for (int s = 0; s < NKS; ++s) {
;           bf16x8 a = *(const bf16x8*)(ks + (kb * 32 + r) * KST + 16 * s + 8 * hh);
;           st[kb] = MFMA32(a, qf[s], st[kb]);
;         }
;       }
;       float mx = -INFINITY;
; #pragma unroll
;       for (int kb = 0; kb < 2; ++kb)
; #pragma unroll
;         for (int i = 0; i < 16; ++i) {
;           float v = st[kb][i];
;           if (MASK) {
;             int kg = k0 + kb * 32 + (i & 3) + 8 * (i >> 2) + 4 * hh;
;             bool ok = kg <= qrow;
;             if (WIN) ok = ok && (qrow - kg < 128);
;             v = ok ? v : -INFINITY;
;             st[kb][i] = v;
;           }
;           mx = fmaxf(mx, v);
;         }
;       mx = fmaxf(mx, __shfl_xor(mx, 32));
;       const float mn = fmaxf(m, mx);
;       if (__any(mn != m)) {
;         const float alpha = __builtin_amdgcn_exp2f((m - mn) * qscale);
;         lsum *= alpha;
; #pragma unroll
;         for (int i = 0; i < 16; ++i) { o[0][i] *= alpha; o[1][i] *= alpha; }
;       }
.LBB0_258:
	s_and_saveexec_b64 s[24:25], s[8:9]
	s_cbranch_execz .LBB0_262
	ds_read_b128 v[182:185], v155 offset:22528
	ds_read_b128 v[186:189], v155 offset:22560
	ds_read_b128 v[190:193], v155 offset:22592
	ds_read_b128 v[194:197], v155 offset:29216
	ds_read_b128 v[198:201], v155 offset:22624
	ds_read_b128 v[202:205], v155 offset:22656
	ds_read_b128 v[206:209], v155 offset:22688
	ds_read_b128 v[210:213], v155 offset:29184
	ds_read_b128 v[214:217], v155 offset:29248
	ds_read_b128 v[218:221], v155 offset:29280
	ds_read_b128 v[222:225], v155 offset:29312
	ds_read_b128 v[226:229], v155 offset:29344
	s_nop 7
	v_and_b32_e32 v159, 64, v172
	v_xor_b32_e32 v158, 32, v172
	v_add_u32_e32 v159, 64, v159
	s_waitcnt lgkmcnt(11)
	v_mfma_f32_32x32x16_bf16 v[34:49], v[182:185], v[66:69], 0
	v_cmp_lt_i32_e32 vcc, v158, v159
	s_nop 1
	v_cndmask_b32_e32 v158, v172, v158, vcc
	v_lshlrev_b32_e32 v158, 2, v158
	s_waitcnt lgkmcnt(10)
	v_mfma_f32_32x32x16_bf16 v[34:49], v[186:189], v[70:73], v[34:49]
	s_waitcnt lgkmcnt(9)
	v_mfma_f32_32x32x16_bf16 v[34:49], v[190:193], v[74:77], v[34:49]
	s_waitcnt lgkmcnt(7)
	v_mfma_f32_32x32x16_bf16 v[34:49], v[198:201], v[78:81], v[34:49]
	s_waitcnt lgkmcnt(6)
	v_mfma_f32_32x32x16_bf16 v[34:49], v[202:205], v[82:85], v[34:49]
	s_waitcnt lgkmcnt(5)
	v_mfma_f32_32x32x16_bf16 v[34:49], v[206:209], v[86:89], v[34:49]
	s_waitcnt lgkmcnt(4)
	v_mfma_f32_32x32x16_bf16 v[50:65], v[210:213], v[66:69], 0
	s_nop 8
	s_nop 0
	v_max3_f32 v0, v34, s94, v35
	v_max3_f32 v0, v0, v36, v37
	v_max3_f32 v0, v0, v38, v39
	v_max3_f32 v0, v0, v40, v41
	v_max3_f32 v0, v0, v42, v43
	v_max3_f32 v0, v0, v44, v45
	v_max3_f32 v0, v0, v46, v47
	v_mfma_f32_32x32x16_bf16 v[50:65], v[194:197], v[70:73], v[50:65]
	v_max3_f32 v0, v0, v48, v49
	s_waitcnt lgkmcnt(3)
	v_mfma_f32_32x32x16_bf16 v[50:65], v[214:217], v[74:77], v[50:65]
	s_waitcnt lgkmcnt(2)
	v_mfma_f32_32x32x16_bf16 v[50:65], v[218:221], v[78:81], v[50:65]
	s_waitcnt lgkmcnt(1)
	v_mfma_f32_32x32x16_bf16 v[50:65], v[222:225], v[82:85], v[50:65]
	s_waitcnt lgkmcnt(0)
	v_mfma_f32_32x32x16_bf16 v[50:65], v[226:229], v[86:89], v[50:65]
	s_nop 11
	v_max3_f32 v0, v0, v50, v51
	v_max3_f32 v0, v0, v52, v53
	v_max3_f32 v0, v0, v54, v55
	v_max3_f32 v0, v0, v56, v57
	v_max3_f32 v0, v0, v58, v59
	v_max3_f32 v0, v0, v60, v61
	v_max3_f32 v0, v0, v62, v63
	v_max3_f32 v0, v0, v64, v65
	v_mov_b32_e32 v158, v0
	s_nop 1
	v_permlane32_swap_b32 v158, v0
	s_waitcnt lgkmcnt(0)
	v_max3_f32 v0, v157, v0, v158
	v_cmp_neq_f32_e32 vcc, v0, v157
	s_cbranch_vccz .LBB0_261
	v_sub_f32_e32 v158, v157, v0
	v_mul_f32_e32 v158, 0x3e16c740, v158
	v_exp_f32_e32 v158, v158
	s_nop 0
	v_mul_f32_e32 v142, v142, v158
	v_pk_mul_f32 v[32:33], v[32:33], v[158:159] op_sel_hi:[1,0]
	v_pk_mul_f32 v[30:31], v[30:31], v[158:159] op_sel_hi:[1,0]
	v_pk_mul_f32 v[28:29], v[28:29], v[158:159] op_sel_hi:[1,0]
	v_pk_mul_f32 v[26:27], v[26:27], v[158:159] op_sel_hi:[1,0]
	v_pk_mul_f32 v[24:25], v[24:25], v[158:159] op_sel_hi:[1,0]
	v_pk_mul_f32 v[22:23], v[22:23], v[158:159] op_sel_hi:[1,0]
	v_pk_mul_f32 v[20:21], v[20:21], v[158:159] op_sel_hi:[1,0]
	v_pk_mul_f32 v[18:19], v[18:19], v[158:159] op_sel_hi:[1,0]
	v_pk_mul_f32 v[16:17], v[16:17], v[158:159] op_sel_hi:[1,0]
	v_pk_mul_f32 v[14:15], v[14:15], v[158:159] op_sel_hi:[1,0]
	v_pk_mul_f32 v[12:13], v[12:13], v[158:159] op_sel_hi:[1,0]
	v_pk_mul_f32 v[10:11], v[10:11], v[158:159] op_sel_hi:[1,0]
	v_pk_mul_f32 v[8:9], v[8:9], v[158:159] op_sel_hi:[1,0]
	v_pk_mul_f32 v[6:7], v[6:7], v[158:159] op_sel_hi:[1,0]
	v_pk_mul_f32 v[4:5], v[4:5], v[158:159] op_sel_hi:[1,0]
	v_pk_mul_f32 v[2:3], v[2:3], v[158:159] op_sel_hi:[1,0]
; DI unsigned pack2(float a, float b) { unsigned r; asm("v_cvt_pk_bf16_f32 %0, %1, %2\n\ts_nop 1" : "=v"(r) : "v"(a), "v"(b)); return r; }
; #define MFMA32(a, b, c) __builtin_amdgcn_mfma_f32_32x32x16_bf16((a), (b), (c), 0, 0, 0)
; template <int DQK, bool WIN>
; DI void attn_item(const u16* __restrict__ Qb, int ldq, const u16* __restrict__ Kb, int ldk, const u16* __restrict__ Vtb, int qb,
;                   float qscale, float sink2, const u16* __restrict__ zb, int ldz, u16* __restrict__ ob, int ldo, u16* lds) {
;     ...
;       const float nb = -mn * qscale;
;       float ps = 0.f;
; #pragma unroll
;       for (int kb = 0; kb < 2; ++kb)
; #pragma unroll
;         for (int i = 0; i < 16; ++i) { float pv = __builtin_amdgcn_exp2f(fmaf(st[kb][i], qscale, nb)); st[kb][i] = pv; ps += pv; }
;       lsum += ps;
; #pragma unroll
;       for (int kb = 0; kb < 2; ++kb)
; #pragma unroll
;         for (int s2 = 0; s2 < 2; ++s2) {
;           union { bf16x8 v; unsigned u[4]; } pf;
; #pragma unroll
;           for (int j = 0; j < 4; ++j) pf.u[j] = pack2(st[kb][8 * s2 + 2 * j], st[kb][8 * s2 + 2 * j + 1]);
; #pragma unroll
;           for (int vb = 0; vb < 2; ++vb) {
;             const bf16x8 vf = *(const bf16x8*)(vs + (vb * 32 + r) * 72 + (kb * 2 + s2) * 16 + hh * 8);
;             o[vb] = MFMA32(vf, pf.v, o[vb]);
;           }
;         }
;     ...
;   for (int kt = kt_lo; kt <= kt_hi; kt += 2) {
;     if (kt + 2 <= kt_hi) gload(rkA, rvA, kt + 2);
;     if (WIN || kt >= 2 * qb) tile_body(kt, 0, std::true_type{}); else tile_body(kt, 0, std::false_type{});
;     swrite(rkB, rvB, 1);
;     __syncthreads();
;     if (kt + 3 <= kt_hi) gload(rkB, rvB, kt + 3);
;     if (WIN || kt + 1 >= 2 * qb) tile_body(kt + 1, 1, std::true_type{}); else tile_body(kt + 1, 1, std::false_type{});
;     if (kt + 2 <= kt_hi) swrite(rkA, rvA, 0);
;     __syncthreads();
.LBB0_261:
	ds_read_b128 v[186:189], v156 offset:35840
	ds_read_b128 v[190:193], v156 offset:35872
	ds_read_b128 v[194:197], v156 offset:40448
	ds_read_b128 v[198:201], v156 offset:40480
	ds_read_b128 v[202:205], v156 offset:35904
	ds_read_b128 v[206:209], v156 offset:40512
	ds_read_b128 v[210:213], v156 offset:35936
	ds_read_b128 v[214:217], v156 offset:40544
	v_mul_f32_e32 v158, 0xbe16c740, v0
	v_fmamk_f32 v34, v34, 0x3e16c740, v158
	v_exp_f32_e32 v34, v34
	v_fmamk_f32 v35, v35, 0x3e16c740, v158
	v_exp_f32_e32 v35, v35
	v_fmamk_f32 v36, v36, 0x3e16c740, v158
	v_exp_f32_e32 v36, v36
	v_fmamk_f32 v37, v37, 0x3e16c740, v158
	v_exp_f32_e32 v37, v37
	v_fmamk_f32 v38, v38, 0x3e16c740, v158
	v_add_f32_e32 v157, 0, v34
	v_exp_f32_e32 v38, v38
	v_fmamk_f32 v39, v39, 0x3e16c740, v158
	v_add_f32_e32 v157, v35, v157
	v_exp_f32_e32 v39, v39
	v_fmamk_f32 v40, v40, 0x3e16c740, v158
	v_add_f32_e32 v157, v36, v157
	v_exp_f32_e32 v40, v40
	v_fmamk_f32 v41, v41, 0x3e16c740, v158
	v_add_f32_e32 v157, v37, v157
	v_exp_f32_e32 v41, v41
	v_fmamk_f32 v42, v42, 0x3e16c740, v158
	v_add_f32_e32 v157, v38, v157
	v_exp_f32_e32 v42, v42
	v_fmamk_f32 v43, v43, 0x3e16c740, v158
	v_add_f32_e32 v157, v39, v157
	v_exp_f32_e32 v43, v43
	v_fmamk_f32 v44, v44, 0x3e16c740, v158
	v_add_f32_e32 v157, v40, v157
	v_exp_f32_e32 v44, v44
	v_fmamk_f32 v45, v45, 0x3e16c740, v158
	v_add_f32_e32 v157, v41, v157
	v_exp_f32_e32 v45, v45
	v_fmamk_f32 v46, v46, 0x3e16c740, v158
	v_add_f32_e32 v157, v42, v157
	v_exp_f32_e32 v46, v46
	v_fmamk_f32 v47, v47, 0x3e16c740, v158
	v_add_f32_e32 v157, v43, v157
	v_exp_f32_e32 v47, v47
	v_fmamk_f32 v48, v48, 0x3e16c740, v158
	v_add_f32_e32 v157, v44, v157
	v_exp_f32_e32 v48, v48
	v_fmamk_f32 v49, v49, 0x3e16c740, v158
	v_add_f32_e32 v157, v45, v157
	v_exp_f32_e32 v49, v49
	v_fmamk_f32 v50, v50, 0x3e16c740, v158
	v_add_f32_e32 v157, v46, v157
	v_exp_f32_e32 v159, v50
	v_add_f32_e32 v157, v47, v157
	v_add_f32_e32 v157, v48, v157
	v_add_f32_e32 v157, v49, v157
	v_fmamk_f32 v51, v51, 0x3e16c740, v158
	v_add_f32_e32 v50, v159, v157
	v_exp_f32_e32 v157, v51
	v_fmamk_f32 v51, v52, 0x3e16c740, v158
	v_exp_f32_e32 v160, v51
	v_fmamk_f32 v51, v53, 0x3e16c740, v158
	v_exp_f32_e32 v161, v51
	v_fmamk_f32 v51, v54, 0x3e16c740, v158
	v_exp_f32_e32 v162, v51
	v_fmamk_f32 v51, v55, 0x3e16c740, v158
	v_add_f32_e32 v50, v157, v50
	v_exp_f32_e32 v164, v51
	v_fmamk_f32 v51, v56, 0x3e16c740, v158
	v_add_f32_e32 v50, v160, v50
	v_exp_f32_e32 v165, v51
	v_fmamk_f32 v51, v57, 0x3e16c740, v158
	v_add_f32_e32 v50, v161, v50
	v_exp_f32_e32 v166, v51
	v_fmamk_f32 v51, v58, 0x3e16c740, v158
	v_add_f32_e32 v50, v162, v50
	v_exp_f32_e32 v167, v51
	v_fmamk_f32 v51, v59, 0x3e16c740, v158
	v_add_f32_e32 v50, v164, v50
	v_exp_f32_e32 v182, v51
	v_fmamk_f32 v51, v60, 0x3e16c740, v158
	v_add_f32_e32 v50, v165, v50
	v_exp_f32_e32 v183, v51
	v_fmamk_f32 v51, v61, 0x3e16c740, v158
	v_add_f32_e32 v50, v166, v50
	v_exp_f32_e32 v184, v51
	v_fmamk_f32 v51, v62, 0x3e16c740, v158
	v_add_f32_e32 v50, v167, v50
	v_exp_f32_e32 v62, v51
	v_fmamk_f32 v51, v63, 0x3e16c740, v158
	v_add_f32_e32 v50, v182, v50
	v_exp_f32_e32 v63, v51
	v_fmamk_f32 v51, v64, 0x3e16c740, v158
	v_add_f32_e32 v50, v183, v50
	v_exp_f32_e32 v64, v51
	v_fmac_f32_e32 v158, 0x3e16c740, v65
	v_add_f32_e32 v50, v184, v50
	v_exp_f32_e32 v65, v158
	v_add_f32_e32 v50, v62, v50
	v_add_f32_e32 v50, v63, v50
	v_add_f32_e32 v50, v64, v50
	v_add_f32_e32 v50, v65, v50
	v_add_f32_e32 v142, v50, v142
	v_cvt_pk_bf16_f32 v50, v34, v35
	v_cvt_pk_bf16_f32 v51, v36, v37
	v_cvt_pk_bf16_f32 v52, v38, v39
	v_cvt_pk_bf16_f32 v53, v40, v41
	s_waitcnt lgkmcnt(7)
	s_nop 0
	v_mfma_f32_32x32x16_bf16 v[18:33], v[186:189], v[50:53], v[18:33]
	s_waitcnt lgkmcnt(5)
	v_mfma_f32_32x32x16_bf16 v[2:17], v[194:197], v[50:53], v[2:17]
	v_cvt_pk_bf16_f32 v50, v42, v43
	v_cvt_pk_bf16_f32 v51, v44, v45
	v_cvt_pk_bf16_f32 v52, v46, v47
	v_cvt_pk_bf16_f32 v53, v48, v49
	s_waitcnt lgkmcnt(4)
	s_nop 0
	v_mfma_f32_32x32x16_bf16 v[2:17], v[198:201], v[50:53], v[2:17]
	v_mfma_f32_32x32x16_bf16 v[18:33], v[190:193], v[50:53], v[18:33]
	v_cvt_pk_bf16_f32 v50, v159, v157
	v_cvt_pk_bf16_f32 v51, v160, v161
	v_cvt_pk_bf16_f32 v52, v162, v164
	v_cvt_pk_bf16_f32 v53, v165, v166
	v_mov_b32_e32 v157, v0
	s_waitcnt lgkmcnt(3)
	v_mfma_f32_32x32x16_bf16 v[18:33], v[202:205], v[50:53], v[18:33]
	s_waitcnt lgkmcnt(2)
	v_mfma_f32_32x32x16_bf16 v[2:17], v[206:209], v[50:53], v[2:17]
	v_cvt_pk_bf16_f32 v50, v167, v182
	v_cvt_pk_bf16_f32 v51, v183, v184
	v_cvt_pk_bf16_f32 v52, v62, v63
	v_cvt_pk_bf16_f32 v53, v64, v65
	s_waitcnt lgkmcnt(1)
	s_nop 0
	v_mfma_f32_32x32x16_bf16 v[18:33], v[210:213], v[50:53], v[18:33]
	s_waitcnt lgkmcnt(0)
	v_mfma_f32_32x32x16_bf16 v[2:17], v[214:217], v[50:53], v[2:17]
.LBB0_262:
	s_or_b64 exec, exec, s[24:25]
	s_andn2_b64 vcc, exec, s[22:23]
	s_cbranch_vccz .LBB0_254
	s_branch .LBB0_255
